# static s_setprio 1 for waves 4-7 during the attention phases P5-P6 (reset at P7)
# speedup vs baseline: 1.0112x; 1.0036x over previous
.LBB0_576:
	v_readlane_b32 s0, v235, 17
	s_cmp_lt_u32 s0, 4
	s_cbranch_scc1 .Lprio5
	s_setprio 1

.LBB0_745:
	s_barrier
	s_setprio 0
	v_mbcnt_lo_u32_b32 v2, -1, 0
	v_mbcnt_hi_u32_b32 v2, -1, v2
	v_readlane_b32 s0, v235, 17
	s_lshl_b32 s0, s0, 6
	v_add_u32_e32 v2, s0, v2
	v_lshlrev_b32_e32 v2, 4, v2
	v_mov_b32_e32 v3, 0
	s_bfe_u32 s0, s96, 0x20001
	s_lshl_b32 s0, s0, 21
	v_readlane_b32 s2, v235, 48
	v_readlane_b32 s3, v235, 49
	v_readlane_b32 s4, v235, 46
	v_readlane_b32 s5, v235, 47
	s_add_u32 s2, s2, s0
	s_addc_u32 s3, s3, 0
	s_add_u32 s4, s4, s0
	s_addc_u32 s5, s5, 0
	v_lshl_add_u64 v[4:5], s[2:3], 0, v[2:3]
	v_lshl_add_u64 v[6:7], s[4:5], 0, v[2:3]
	global_load_dwordx4 v[8:11], v[4:5], off
	global_load_dwordx4 v[12:15], v[6:7], off
	s_waitcnt vmcnt(1)
	ds_write_b128 v2, v[8:11]
	s_waitcnt vmcnt(0)
	ds_write_b128 v2, v[12:15] offset:8192
	v_mbcnt_lo_u32_b32 v0, -1, 0
	v_mbcnt_hi_u32_b32 v0, -1, v0
	v_readlane_b32 s2, v234, 2
	v_add_u32_e32 v0, s78, v0
	v_ashrrev_i32_e32 v1, 31, v0
	v_readlane_b32 s3, v234, 3
	s_add_i32 s40, 0, 0x12000
	s_add_i32 s0, s78, 0x200
	v_lshl_add_u64 v[2:3], v[0:1], 2, s[2:3]
	global_load_dword v1, v[2:3], off
	v_lshl_add_u32 v0, v0, 2, s40
	s_waitcnt vmcnt(0)
	ds_write_b32 v0, v1
	v_mbcnt_lo_u32_b32 v0, -1, 0
	v_mbcnt_hi_u32_b32 v0, -1, v0
	s_nop 0
	v_add_u32_e32 v0, s0, v0
	v_ashrrev_i32_e32 v1, 31, v0
	v_lshl_add_u64 v[2:3], v[0:1], 2, s[2:3]
	global_load_dword v1, v[2:3], off
	v_lshl_add_u32 v0, v0, 2, s40
	s_add_i32 s0, s78, 0x400
	s_waitcnt vmcnt(0)
	ds_write_b32 v0, v1
	v_mbcnt_lo_u32_b32 v0, -1, 0
	v_mbcnt_hi_u32_b32 v0, -1, v0
	s_nop 0
	v_add_u32_e32 v0, s0, v0
	v_ashrrev_i32_e32 v1, 31, v0
	v_lshl_add_u64 v[2:3], v[0:1], 2, s[2:3]
	global_load_dword v1, v[2:3], off
	v_lshl_add_u32 v0, v0, 2, s40
	s_add_i32 s0, s78, 0x600
	s_waitcnt vmcnt(0)
	ds_write_b32 v0, v1
	v_mbcnt_lo_u32_b32 v0, -1, 0
	v_mbcnt_hi_u32_b32 v0, -1, v0
	s_nop 0
	v_add_u32_e32 v0, s0, v0
	v_ashrrev_i32_e32 v1, 31, v0
	v_lshl_add_u64 v[2:3], v[0:1], 2, s[2:3]
	global_load_dword v1, v[2:3], off
	v_lshl_add_u32 v0, v0, 2, s40
	s_add_i32 s0, s78, 0x800
	s_waitcnt vmcnt(0)
	ds_write_b32 v0, v1
	v_mbcnt_lo_u32_b32 v0, -1, 0
	v_mbcnt_hi_u32_b32 v0, -1, v0
	s_nop 0
	v_add_u32_e32 v0, s0, v0
	v_ashrrev_i32_e32 v1, 31, v0
	v_lshl_add_u64 v[2:3], v[0:1], 2, s[2:3]
	global_load_dword v1, v[2:3], off
	v_lshl_add_u32 v0, v0, 2, s40
	s_add_i32 s0, s78, 0xa00
	s_waitcnt vmcnt(0)
	ds_write_b32 v0, v1
	v_mbcnt_lo_u32_b32 v0, -1, 0
	v_mbcnt_hi_u32_b32 v0, -1, v0
	s_nop 0
	v_add_u32_e32 v0, s0, v0
	v_ashrrev_i32_e32 v1, 31, v0
	v_lshl_add_u64 v[2:3], v[0:1], 2, s[2:3]
	global_load_dword v1, v[2:3], off
	v_lshl_add_u32 v0, v0, 2, s40
	s_add_i32 s0, s78, 0xc00
	s_waitcnt vmcnt(0)
	ds_write_b32 v0, v1
	v_mbcnt_lo_u32_b32 v0, -1, 0
	v_mbcnt_hi_u32_b32 v0, -1, v0
	s_nop 0
	v_add_u32_e32 v0, s0, v0
	v_ashrrev_i32_e32 v1, 31, v0
	v_lshl_add_u64 v[2:3], v[0:1], 2, s[2:3]
	global_load_dword v1, v[2:3], off
	v_lshl_add_u32 v0, v0, 2, s40
	s_add_i32 s0, s78, 0xe00
	s_cmpk_lg_i32 s92, 0x100
	s_waitcnt vmcnt(0)
	ds_write_b32 v0, v1
	v_mbcnt_lo_u32_b32 v0, -1, 0
	v_mbcnt_hi_u32_b32 v0, -1, v0
	s_nop 0
	v_add_u32_e32 v0, s0, v0
	v_ashrrev_i32_e32 v1, 31, v0
	v_lshl_add_u64 v[2:3], v[0:1], 2, s[2:3]
	global_load_dword v1, v[2:3], off
	v_lshl_add_u32 v0, v0, 2, s40
	s_mov_b64 s[0:1], -1
	s_waitcnt vmcnt(0)
	ds_write_b32 v0, v1
	s_waitcnt lgkmcnt(0)
	s_barrier
	s_cbranch_scc0 .LBB0_779
	v_readlane_b32 s4, v235, 44
	s_cmp_gt_i32 s4, 0xffff
	v_readlane_b32 s5, v235, 45
	s_cbranch_scc1 .LBB0_778
	v_mov_b32_e32 v1, 0
	s_movk_i32 s1, 0x1000
	s_mov_b32 s0, 0x3d800000
	s_mov_b32 s33, 0xf149f2ca
	s_mov_b32 s41, 0xefa18f08
	s_mov_b32 s42, 0x3c800000
	s_movk_i32 s43, 0x2000
	v_mov_b32_e32 v118, 0x461c4000
	v_mov_b32_e32 v119, 0x1ff
	v_mov_b32_e32 v120, 0xf149f2ca
	s_branch .LBB0_749
